# next-unit row-scale partial-sum loads issued earlier inside the fused epilogue (epilogue split in three parts around the baseline's reduce code)
# speedup vs baseline: 1.0058x; 1.0058x over previous
.Lfe_join:
	s_mov_b64 exec, -1
	s_waitcnt lgkmcnt(0)
	s_barrier
	s_mov_b32 exec_lo, 0xc000c000
	s_mov_b32 exec_hi, 0xc000c000
	ds_read_b128 v[246:249], v234 offset:0
	ds_read_b128 v[250:253], v234 offset:16
	s_mov_b64 exec, -1
	s_waitcnt vmcnt(12)
	v_fma_f32 v176, v132, v108, v156
	v_fma_f32 v177, v133, v109, v157
	v_fma_f32 v178, v134, v110, v158
	v_fma_f32 v179, v135, v111, v159
	v_fma_f32 v182, v136, v104, v160
	v_fma_f32 v183, v137, v105, v161
	v_fma_f32 v184, v138, v106, v162
	v_fma_f32 v185, v139, v107, v163
	v_fmac_f32_dpp v176, v108, v140 row_shr:1 row_mask:0xf bank_mask:0xf
	v_fmac_f32_dpp v177, v109, v141 row_shr:1 row_mask:0xf bank_mask:0xf
	v_fmac_f32_dpp v178, v110, v142 row_shr:1 row_mask:0xf bank_mask:0xf
	v_fmac_f32_dpp v179, v111, v143 row_shr:1 row_mask:0xf bank_mask:0xf
	v_fmac_f32_dpp v182, v104, v144 row_shr:1 row_mask:0xf bank_mask:0xf
	v_fmac_f32_dpp v183, v105, v145 row_shr:1 row_mask:0xf bank_mask:0xf
	v_fmac_f32_dpp v184, v106, v146 row_shr:1 row_mask:0xf bank_mask:0xf
	v_fmac_f32_dpp v185, v107, v147 row_shr:1 row_mask:0xf bank_mask:0xf
	v_fmac_f32_dpp v176, v108, v148 row_shr:2 row_mask:0xf bank_mask:0xf
	v_fmac_f32_dpp v177, v109, v149 row_shr:2 row_mask:0xf bank_mask:0xf
	v_fmac_f32_dpp v178, v110, v150 row_shr:2 row_mask:0xf bank_mask:0xf
	v_fmac_f32_dpp v179, v111, v151 row_shr:2 row_mask:0xf bank_mask:0xf
	v_fmac_f32_dpp v182, v104, v152 row_shr:2 row_mask:0xf bank_mask:0xf
	v_fmac_f32_dpp v183, v105, v153 row_shr:2 row_mask:0xf bank_mask:0xf
	v_fmac_f32_dpp v184, v106, v154 row_shr:2 row_mask:0xf bank_mask:0xf
	v_fmac_f32_dpp v185, v107, v155 row_shr:2 row_mask:0xf bank_mask:0xf
	v_fmac_f32_dpp v176, v116, v140 row_shl:15 row_mask:0xf bank_mask:0xf
	v_fmac_f32_dpp v177, v117, v141 row_shl:15 row_mask:0xf bank_mask:0xf
	v_fmac_f32_dpp v178, v118, v142 row_shl:15 row_mask:0xf bank_mask:0xf
	v_fmac_f32_dpp v179, v119, v143 row_shl:15 row_mask:0xf bank_mask:0xf
	v_fmac_f32_dpp v182, v112, v144 row_shl:15 row_mask:0xf bank_mask:0xf
	v_fmac_f32_dpp v183, v113, v145 row_shl:15 row_mask:0xf bank_mask:0xf
	v_fmac_f32_dpp v184, v114, v146 row_shl:15 row_mask:0xf bank_mask:0xf
	v_fmac_f32_dpp v185, v115, v147 row_shl:15 row_mask:0xf bank_mask:0xf
	v_fmac_f32_dpp v176, v116, v148 row_shl:14 row_mask:0xf bank_mask:0xf
	v_fmac_f32_dpp v177, v117, v149 row_shl:14 row_mask:0xf bank_mask:0xf
	v_fmac_f32_dpp v178, v118, v150 row_shl:14 row_mask:0xf bank_mask:0xf
	v_fmac_f32_dpp v179, v119, v151 row_shl:14 row_mask:0xf bank_mask:0xf
	v_fmac_f32_dpp v182, v112, v152 row_shl:14 row_mask:0xf bank_mask:0xf
	v_fmac_f32_dpp v183, v113, v153 row_shl:14 row_mask:0xf bank_mask:0xf
	v_fmac_f32_dpp v184, v114, v154 row_shl:14 row_mask:0xf bank_mask:0xf
	v_fmac_f32_dpp v185, v115, v155 row_shl:14 row_mask:0xf bank_mask:0xf
	v_fma_f32 v108, v132, v116, v156
	v_fma_f32 v109, v133, v117, v157
	v_fma_f32 v110, v134, v118, v158
	v_fma_f32 v111, v135, v119, v159
	v_fma_f32 v104, v136, v112, v160
	v_fma_f32 v105, v137, v113, v161
	v_fma_f32 v106, v138, v114, v162
	v_fma_f32 v107, v139, v115, v163
	v_fmac_f32_dpp v108, v116, v140 row_shr:1 row_mask:0xf bank_mask:0xf
	v_fmac_f32_dpp v109, v117, v141 row_shr:1 row_mask:0xf bank_mask:0xf
	v_fmac_f32_dpp v110, v118, v142 row_shr:1 row_mask:0xf bank_mask:0xf
	v_fmac_f32_dpp v111, v119, v143 row_shr:1 row_mask:0xf bank_mask:0xf
	v_fmac_f32_dpp v104, v112, v144 row_shr:1 row_mask:0xf bank_mask:0xf
	v_fmac_f32_dpp v105, v113, v145 row_shr:1 row_mask:0xf bank_mask:0xf
	v_fmac_f32_dpp v106, v114, v146 row_shr:1 row_mask:0xf bank_mask:0xf
	v_fmac_f32_dpp v107, v115, v147 row_shr:1 row_mask:0xf bank_mask:0xf
	v_fmac_f32_dpp v108, v116, v148 row_shr:2 row_mask:0xf bank_mask:0xf
	v_fmac_f32_dpp v109, v117, v149 row_shr:2 row_mask:0xf bank_mask:0xf
	v_fmac_f32_dpp v110, v118, v150 row_shr:2 row_mask:0xf bank_mask:0xf
	v_fmac_f32_dpp v111, v119, v151 row_shr:2 row_mask:0xf bank_mask:0xf
	v_fmac_f32_dpp v104, v112, v152 row_shr:2 row_mask:0xf bank_mask:0xf
	v_fmac_f32_dpp v105, v113, v153 row_shr:2 row_mask:0xf bank_mask:0xf
	v_fmac_f32_dpp v106, v114, v154 row_shr:2 row_mask:0xf bank_mask:0xf
	v_fmac_f32_dpp v107, v115, v155 row_shr:2 row_mask:0xf bank_mask:0xf
	v_fmac_f32_dpp v108, v124, v140 row_shl:15 row_mask:0xf bank_mask:0xf
	v_fmac_f32_dpp v109, v125, v141 row_shl:15 row_mask:0xf bank_mask:0xf
	v_fmac_f32_dpp v110, v126, v142 row_shl:15 row_mask:0xf bank_mask:0xf
	v_fmac_f32_dpp v111, v127, v143 row_shl:15 row_mask:0xf bank_mask:0xf
	v_fmac_f32_dpp v104, v120, v144 row_shl:15 row_mask:0xf bank_mask:0xf
	v_fmac_f32_dpp v105, v121, v145 row_shl:15 row_mask:0xf bank_mask:0xf
	v_fmac_f32_dpp v106, v122, v146 row_shl:15 row_mask:0xf bank_mask:0xf
	v_fmac_f32_dpp v107, v123, v147 row_shl:15 row_mask:0xf bank_mask:0xf
	v_fmac_f32_dpp v108, v124, v148 row_shl:14 row_mask:0xf bank_mask:0xf
	v_fmac_f32_dpp v109, v125, v149 row_shl:14 row_mask:0xf bank_mask:0xf
	v_fmac_f32_dpp v110, v126, v150 row_shl:14 row_mask:0xf bank_mask:0xf
	v_fmac_f32_dpp v111, v127, v151 row_shl:14 row_mask:0xf bank_mask:0xf
	v_fmac_f32_dpp v104, v120, v152 row_shl:14 row_mask:0xf bank_mask:0xf
	v_fmac_f32_dpp v105, v121, v153 row_shl:14 row_mask:0xf bank_mask:0xf
	v_fmac_f32_dpp v106, v122, v154 row_shl:14 row_mask:0xf bank_mask:0xf
	v_fmac_f32_dpp v107, v123, v155 row_shl:14 row_mask:0xf bank_mask:0xf
	v_fma_f32 v116, v132, v124, v156
	v_fma_f32 v117, v133, v125, v157
	v_fma_f32 v118, v134, v126, v158
	v_fma_f32 v119, v135, v127, v159
	v_fma_f32 v112, v136, v120, v160
	v_fma_f32 v113, v137, v121, v161
	v_fma_f32 v114, v138, v122, v162
	v_fma_f32 v115, v139, v123, v163
	v_fmac_f32_dpp v116, v124, v140 row_shr:1 row_mask:0xf bank_mask:0xf
	v_fmac_f32_dpp v117, v125, v141 row_shr:1 row_mask:0xf bank_mask:0xf
	v_fmac_f32_dpp v118, v126, v142 row_shr:1 row_mask:0xf bank_mask:0xf
	v_fmac_f32_dpp v119, v127, v143 row_shr:1 row_mask:0xf bank_mask:0xf
	v_fmac_f32_dpp v112, v120, v144 row_shr:1 row_mask:0xf bank_mask:0xf
	v_fmac_f32_dpp v113, v121, v145 row_shr:1 row_mask:0xf bank_mask:0xf
	v_fmac_f32_dpp v114, v122, v146 row_shr:1 row_mask:0xf bank_mask:0xf
	v_fmac_f32_dpp v115, v123, v147 row_shr:1 row_mask:0xf bank_mask:0xf
	v_fmac_f32_dpp v116, v124, v148 row_shr:2 row_mask:0xf bank_mask:0xf
	v_fmac_f32_dpp v117, v125, v149 row_shr:2 row_mask:0xf bank_mask:0xf
	v_fmac_f32_dpp v118, v126, v150 row_shr:2 row_mask:0xf bank_mask:0xf
	v_fmac_f32_dpp v119, v127, v151 row_shr:2 row_mask:0xf bank_mask:0xf
	v_fmac_f32_dpp v112, v120, v152 row_shr:2 row_mask:0xf bank_mask:0xf
	v_fmac_f32_dpp v113, v121, v153 row_shr:2 row_mask:0xf bank_mask:0xf
	v_fmac_f32_dpp v114, v122, v154 row_shr:2 row_mask:0xf bank_mask:0xf
	v_fmac_f32_dpp v115, v123, v155 row_shr:2 row_mask:0xf bank_mask:0xf
	v_fmac_f32_dpp v116, v8, v140 row_shl:15 row_mask:0xf bank_mask:0xf
	v_fmac_f32_dpp v117, v9, v141 row_shl:15 row_mask:0xf bank_mask:0xf
	v_fmac_f32_dpp v118, v10, v142 row_shl:15 row_mask:0xf bank_mask:0xf
	v_fmac_f32_dpp v119, v11, v143 row_shl:15 row_mask:0xf bank_mask:0xf
	v_fmac_f32_dpp v112, v128, v144 row_shl:15 row_mask:0xf bank_mask:0xf
	v_fmac_f32_dpp v113, v129, v145 row_shl:15 row_mask:0xf bank_mask:0xf
	v_fmac_f32_dpp v114, v130, v146 row_shl:15 row_mask:0xf bank_mask:0xf
	v_fmac_f32_dpp v115, v131, v147 row_shl:15 row_mask:0xf bank_mask:0xf
	v_fmac_f32_dpp v116, v8, v148 row_shl:14 row_mask:0xf bank_mask:0xf
	v_fmac_f32_dpp v117, v9, v149 row_shl:14 row_mask:0xf bank_mask:0xf
	v_fmac_f32_dpp v118, v10, v150 row_shl:14 row_mask:0xf bank_mask:0xf
	v_fmac_f32_dpp v119, v11, v151 row_shl:14 row_mask:0xf bank_mask:0xf
	v_fmac_f32_dpp v112, v128, v152 row_shl:14 row_mask:0xf bank_mask:0xf
	v_fmac_f32_dpp v113, v129, v153 row_shl:14 row_mask:0xf bank_mask:0xf
	v_fmac_f32_dpp v114, v130, v154 row_shl:14 row_mask:0xf bank_mask:0xf
	v_fmac_f32_dpp v115, v131, v155 row_shl:14 row_mask:0xf bank_mask:0xf
	s_waitcnt lgkmcnt(0)
	v_fma_f32 v124, v132, v8, v156
	v_fma_f32 v125, v133, v9, v157
	v_fma_f32 v126, v134, v10, v158
	v_fma_f32 v127, v135, v11, v159
	v_fma_f32 v120, v136, v128, v160
	v_fma_f32 v121, v137, v129, v161
	v_fma_f32 v122, v138, v130, v162
	v_fma_f32 v123, v139, v131, v163
	v_fmac_f32_dpp v124, v8, v140 row_shr:1 row_mask:0xf bank_mask:0xf
	v_fmac_f32_dpp v125, v9, v141 row_shr:1 row_mask:0xf bank_mask:0xf
	v_fmac_f32_dpp v126, v10, v142 row_shr:1 row_mask:0xf bank_mask:0xf
	v_fmac_f32_dpp v127, v11, v143 row_shr:1 row_mask:0xf bank_mask:0xf
	v_fmac_f32_dpp v120, v128, v144 row_shr:1 row_mask:0xf bank_mask:0xf
	v_fmac_f32_dpp v121, v129, v145 row_shr:1 row_mask:0xf bank_mask:0xf
	v_fmac_f32_dpp v122, v130, v146 row_shr:1 row_mask:0xf bank_mask:0xf
	v_fmac_f32_dpp v123, v131, v147 row_shr:1 row_mask:0xf bank_mask:0xf
	v_fmac_f32_dpp v124, v8, v148 row_shr:2 row_mask:0xf bank_mask:0xf
	v_fmac_f32_dpp v125, v9, v149 row_shr:2 row_mask:0xf bank_mask:0xf
	v_fmac_f32_dpp v126, v10, v150 row_shr:2 row_mask:0xf bank_mask:0xf
	v_fmac_f32_dpp v127, v11, v151 row_shr:2 row_mask:0xf bank_mask:0xf
	v_fmac_f32_dpp v120, v128, v152 row_shr:2 row_mask:0xf bank_mask:0xf
	v_fmac_f32_dpp v121, v129, v153 row_shr:2 row_mask:0xf bank_mask:0xf
	v_fmac_f32_dpp v122, v130, v154 row_shr:2 row_mask:0xf bank_mask:0xf
	v_fmac_f32_dpp v123, v131, v155 row_shr:2 row_mask:0xf bank_mask:0xf
	v_fmac_f32_dpp v124, v246, v140 row_shl:15 row_mask:0xf bank_mask:0xf
	v_fmac_f32_dpp v125, v247, v141 row_shl:15 row_mask:0xf bank_mask:0xf
	v_fmac_f32_dpp v126, v248, v142 row_shl:15 row_mask:0xf bank_mask:0xf
	v_fmac_f32_dpp v127, v249, v143 row_shl:15 row_mask:0xf bank_mask:0xf
	v_fmac_f32_dpp v120, v250, v144 row_shl:15 row_mask:0xf bank_mask:0xf
	v_fmac_f32_dpp v121, v251, v145 row_shl:15 row_mask:0xf bank_mask:0xf
	v_fmac_f32_dpp v122, v252, v146 row_shl:15 row_mask:0xf bank_mask:0xf
	v_fmac_f32_dpp v123, v253, v147 row_shl:15 row_mask:0xf bank_mask:0xf
	v_fmac_f32_dpp v124, v246, v148 row_shl:14 row_mask:0xf bank_mask:0xf
	v_fmac_f32_dpp v125, v247, v149 row_shl:14 row_mask:0xf bank_mask:0xf
	v_fmac_f32_dpp v126, v248, v150 row_shl:14 row_mask:0xf bank_mask:0xf
	v_fmac_f32_dpp v127, v249, v151 row_shl:14 row_mask:0xf bank_mask:0xf
	v_fmac_f32_dpp v120, v250, v152 row_shl:14 row_mask:0xf bank_mask:0xf
	v_fmac_f32_dpp v121, v251, v153 row_shl:14 row_mask:0xf bank_mask:0xf
	v_fmac_f32_dpp v122, v252, v154 row_shl:14 row_mask:0xf bank_mask:0xf
	v_fmac_f32_dpp v123, v253, v155 row_shl:14 row_mask:0xf bank_mask:0xf
	s_mov_b32 exec_lo, 0xc000c000
	s_mov_b32 exec_hi, 0xc000c000
	ds_read_b128 v[246:249], v234 offset:512
	ds_read_b128 v[250:253], v234 offset:528
	s_mov_b64 exec, -1
	s_waitcnt vmcnt(4)
	v_fma_f32 v8, v194, v76, v226
	v_fma_f32 v9, v195, v77, v227
	v_fma_f32 v10, v196, v78, v228
	v_fma_f32 v11, v197, v79, v229
	v_fma_f32 v128, v198, v72, v230
	v_fma_f32 v129, v199, v73, v231
	v_fma_f32 v130, v200, v74, v232
	v_fma_f32 v131, v201, v75, v233
	v_fmac_f32_dpp v8, v76, v202 row_shr:1 row_mask:0xf bank_mask:0xf
	v_fmac_f32_dpp v9, v77, v203 row_shr:1 row_mask:0xf bank_mask:0xf
	v_fmac_f32_dpp v10, v78, v204 row_shr:1 row_mask:0xf bank_mask:0xf
	v_fmac_f32_dpp v11, v79, v205 row_shr:1 row_mask:0xf bank_mask:0xf
	v_fmac_f32_dpp v128, v72, v206 row_shr:1 row_mask:0xf bank_mask:0xf
	v_fmac_f32_dpp v129, v73, v207 row_shr:1 row_mask:0xf bank_mask:0xf
	v_fmac_f32_dpp v130, v74, v208 row_shr:1 row_mask:0xf bank_mask:0xf
	v_fmac_f32_dpp v131, v75, v209 row_shr:1 row_mask:0xf bank_mask:0xf
	v_fmac_f32_dpp v8, v76, v210 row_shr:2 row_mask:0xf bank_mask:0xf
	v_fmac_f32_dpp v9, v77, v211 row_shr:2 row_mask:0xf bank_mask:0xf
	v_fmac_f32_dpp v10, v78, v212 row_shr:2 row_mask:0xf bank_mask:0xf
	v_fmac_f32_dpp v11, v79, v213 row_shr:2 row_mask:0xf bank_mask:0xf
	v_fmac_f32_dpp v128, v72, v214 row_shr:2 row_mask:0xf bank_mask:0xf
	v_fmac_f32_dpp v129, v73, v215 row_shr:2 row_mask:0xf bank_mask:0xf
	v_fmac_f32_dpp v130, v74, v216 row_shr:2 row_mask:0xf bank_mask:0xf
	v_fmac_f32_dpp v131, v75, v217 row_shr:2 row_mask:0xf bank_mask:0xf
	v_fmac_f32_dpp v8, v84, v202 row_shl:15 row_mask:0xf bank_mask:0xf
	v_fmac_f32_dpp v9, v85, v203 row_shl:15 row_mask:0xf bank_mask:0xf
	v_fmac_f32_dpp v10, v86, v204 row_shl:15 row_mask:0xf bank_mask:0xf
	v_fmac_f32_dpp v11, v87, v205 row_shl:15 row_mask:0xf bank_mask:0xf
	v_fmac_f32_dpp v128, v80, v206 row_shl:15 row_mask:0xf bank_mask:0xf
	v_fmac_f32_dpp v129, v81, v207 row_shl:15 row_mask:0xf bank_mask:0xf
	v_fmac_f32_dpp v130, v82, v208 row_shl:15 row_mask:0xf bank_mask:0xf
	v_fmac_f32_dpp v131, v83, v209 row_shl:15 row_mask:0xf bank_mask:0xf
	v_fmac_f32_dpp v8, v84, v210 row_shl:14 row_mask:0xf bank_mask:0xf
	v_fmac_f32_dpp v9, v85, v211 row_shl:14 row_mask:0xf bank_mask:0xf
	v_fmac_f32_dpp v10, v86, v212 row_shl:14 row_mask:0xf bank_mask:0xf
	v_fmac_f32_dpp v11, v87, v213 row_shl:14 row_mask:0xf bank_mask:0xf
	v_fmac_f32_dpp v128, v80, v214 row_shl:14 row_mask:0xf bank_mask:0xf
	v_fmac_f32_dpp v129, v81, v215 row_shl:14 row_mask:0xf bank_mask:0xf
	v_fmac_f32_dpp v130, v82, v216 row_shl:14 row_mask:0xf bank_mask:0xf
	v_fmac_f32_dpp v131, v83, v217 row_shl:14 row_mask:0xf bank_mask:0xf
	v_fma_f32 v76, v194, v84, v226
	v_fma_f32 v77, v195, v85, v227
	v_fma_f32 v78, v196, v86, v228
	v_fma_f32 v79, v197, v87, v229
	v_fma_f32 v72, v198, v80, v230
	v_fma_f32 v73, v199, v81, v231
	v_fma_f32 v74, v200, v82, v232
	v_fma_f32 v75, v201, v83, v233
	v_fmac_f32_dpp v76, v84, v202 row_shr:1 row_mask:0xf bank_mask:0xf
	v_fmac_f32_dpp v77, v85, v203 row_shr:1 row_mask:0xf bank_mask:0xf
	v_fmac_f32_dpp v78, v86, v204 row_shr:1 row_mask:0xf bank_mask:0xf
	v_fmac_f32_dpp v79, v87, v205 row_shr:1 row_mask:0xf bank_mask:0xf
	v_fmac_f32_dpp v72, v80, v206 row_shr:1 row_mask:0xf bank_mask:0xf
	v_fmac_f32_dpp v73, v81, v207 row_shr:1 row_mask:0xf bank_mask:0xf
	v_fmac_f32_dpp v74, v82, v208 row_shr:1 row_mask:0xf bank_mask:0xf
	v_fmac_f32_dpp v75, v83, v209 row_shr:1 row_mask:0xf bank_mask:0xf
	v_fmac_f32_dpp v76, v84, v210 row_shr:2 row_mask:0xf bank_mask:0xf
	v_fmac_f32_dpp v77, v85, v211 row_shr:2 row_mask:0xf bank_mask:0xf
	v_fmac_f32_dpp v78, v86, v212 row_shr:2 row_mask:0xf bank_mask:0xf
	v_fmac_f32_dpp v79, v87, v213 row_shr:2 row_mask:0xf bank_mask:0xf
	v_fmac_f32_dpp v72, v80, v214 row_shr:2 row_mask:0xf bank_mask:0xf
	v_fmac_f32_dpp v73, v81, v215 row_shr:2 row_mask:0xf bank_mask:0xf
	v_fmac_f32_dpp v74, v82, v216 row_shr:2 row_mask:0xf bank_mask:0xf
	v_fmac_f32_dpp v75, v83, v217 row_shr:2 row_mask:0xf bank_mask:0xf
	v_fmac_f32_dpp v76, v92, v202 row_shl:15 row_mask:0xf bank_mask:0xf
	v_fmac_f32_dpp v77, v93, v203 row_shl:15 row_mask:0xf bank_mask:0xf
	v_fmac_f32_dpp v78, v94, v204 row_shl:15 row_mask:0xf bank_mask:0xf
	v_fmac_f32_dpp v79, v95, v205 row_shl:15 row_mask:0xf bank_mask:0xf
	v_fmac_f32_dpp v72, v88, v206 row_shl:15 row_mask:0xf bank_mask:0xf
	v_fmac_f32_dpp v73, v89, v207 row_shl:15 row_mask:0xf bank_mask:0xf
	v_fmac_f32_dpp v74, v90, v208 row_shl:15 row_mask:0xf bank_mask:0xf
	v_fmac_f32_dpp v75, v91, v209 row_shl:15 row_mask:0xf bank_mask:0xf
	v_fmac_f32_dpp v76, v92, v210 row_shl:14 row_mask:0xf bank_mask:0xf
	v_fmac_f32_dpp v77, v93, v211 row_shl:14 row_mask:0xf bank_mask:0xf
	v_fmac_f32_dpp v78, v94, v212 row_shl:14 row_mask:0xf bank_mask:0xf
	v_fmac_f32_dpp v79, v95, v213 row_shl:14 row_mask:0xf bank_mask:0xf
	v_fmac_f32_dpp v72, v88, v214 row_shl:14 row_mask:0xf bank_mask:0xf
	v_fmac_f32_dpp v73, v89, v215 row_shl:14 row_mask:0xf bank_mask:0xf
	v_fmac_f32_dpp v74, v90, v216 row_shl:14 row_mask:0xf bank_mask:0xf
	v_fmac_f32_dpp v75, v91, v217 row_shl:14 row_mask:0xf bank_mask:0xf
	v_fma_f32 v84, v194, v92, v226
	v_fma_f32 v85, v195, v93, v227
	v_fma_f32 v86, v196, v94, v228
	v_fma_f32 v87, v197, v95, v229
	v_fma_f32 v80, v198, v88, v230
	v_fma_f32 v81, v199, v89, v231
	v_fma_f32 v82, v200, v90, v232
	v_fma_f32 v83, v201, v91, v233
	v_fmac_f32_dpp v84, v92, v202 row_shr:1 row_mask:0xf bank_mask:0xf
	v_fmac_f32_dpp v85, v93, v203 row_shr:1 row_mask:0xf bank_mask:0xf
	v_fmac_f32_dpp v86, v94, v204 row_shr:1 row_mask:0xf bank_mask:0xf
	v_fmac_f32_dpp v87, v95, v205 row_shr:1 row_mask:0xf bank_mask:0xf
	v_fmac_f32_dpp v80, v88, v206 row_shr:1 row_mask:0xf bank_mask:0xf
	v_fmac_f32_dpp v81, v89, v207 row_shr:1 row_mask:0xf bank_mask:0xf
	v_fmac_f32_dpp v82, v90, v208 row_shr:1 row_mask:0xf bank_mask:0xf
	v_fmac_f32_dpp v83, v91, v209 row_shr:1 row_mask:0xf bank_mask:0xf
	v_fmac_f32_dpp v84, v92, v210 row_shr:2 row_mask:0xf bank_mask:0xf
	v_fmac_f32_dpp v85, v93, v211 row_shr:2 row_mask:0xf bank_mask:0xf
	v_fmac_f32_dpp v86, v94, v212 row_shr:2 row_mask:0xf bank_mask:0xf
	v_fmac_f32_dpp v87, v95, v213 row_shr:2 row_mask:0xf bank_mask:0xf
	v_fmac_f32_dpp v80, v88, v214 row_shr:2 row_mask:0xf bank_mask:0xf
	v_fmac_f32_dpp v81, v89, v215 row_shr:2 row_mask:0xf bank_mask:0xf
	v_fmac_f32_dpp v82, v90, v216 row_shr:2 row_mask:0xf bank_mask:0xf
	v_fmac_f32_dpp v83, v91, v217 row_shr:2 row_mask:0xf bank_mask:0xf
	v_fmac_f32_dpp v84, v100, v202 row_shl:15 row_mask:0xf bank_mask:0xf
	v_fmac_f32_dpp v85, v101, v203 row_shl:15 row_mask:0xf bank_mask:0xf
	v_fmac_f32_dpp v86, v102, v204 row_shl:15 row_mask:0xf bank_mask:0xf
	v_fmac_f32_dpp v87, v103, v205 row_shl:15 row_mask:0xf bank_mask:0xf
	v_fmac_f32_dpp v80, v96, v206 row_shl:15 row_mask:0xf bank_mask:0xf
	v_fmac_f32_dpp v81, v97, v207 row_shl:15 row_mask:0xf bank_mask:0xf
	v_fmac_f32_dpp v82, v98, v208 row_shl:15 row_mask:0xf bank_mask:0xf
	v_fmac_f32_dpp v83, v99, v209 row_shl:15 row_mask:0xf bank_mask:0xf
	v_fmac_f32_dpp v84, v100, v210 row_shl:14 row_mask:0xf bank_mask:0xf
	v_fmac_f32_dpp v85, v101, v211 row_shl:14 row_mask:0xf bank_mask:0xf
	v_fmac_f32_dpp v86, v102, v212 row_shl:14 row_mask:0xf bank_mask:0xf
	v_fmac_f32_dpp v87, v103, v213 row_shl:14 row_mask:0xf bank_mask:0xf
	v_fmac_f32_dpp v80, v96, v214 row_shl:14 row_mask:0xf bank_mask:0xf
	v_fmac_f32_dpp v81, v97, v215 row_shl:14 row_mask:0xf bank_mask:0xf
	v_fmac_f32_dpp v82, v98, v216 row_shl:14 row_mask:0xf bank_mask:0xf
	v_fmac_f32_dpp v83, v99, v217 row_shl:14 row_mask:0xf bank_mask:0xf
	s_waitcnt lgkmcnt(0)
	v_fma_f32 v92, v194, v100, v226
	v_fma_f32 v93, v195, v101, v227
	v_fma_f32 v94, v196, v102, v228
	v_fma_f32 v95, v197, v103, v229
	v_fma_f32 v88, v198, v96, v230
	v_fma_f32 v89, v199, v97, v231
	v_fma_f32 v90, v200, v98, v232
	v_fma_f32 v91, v201, v99, v233
	v_fmac_f32_dpp v92, v100, v202 row_shr:1 row_mask:0xf bank_mask:0xf
	v_fmac_f32_dpp v93, v101, v203 row_shr:1 row_mask:0xf bank_mask:0xf
	v_fmac_f32_dpp v94, v102, v204 row_shr:1 row_mask:0xf bank_mask:0xf
	v_fmac_f32_dpp v95, v103, v205 row_shr:1 row_mask:0xf bank_mask:0xf
	v_fmac_f32_dpp v88, v96, v206 row_shr:1 row_mask:0xf bank_mask:0xf
	v_fmac_f32_dpp v89, v97, v207 row_shr:1 row_mask:0xf bank_mask:0xf
	v_fmac_f32_dpp v90, v98, v208 row_shr:1 row_mask:0xf bank_mask:0xf
	v_fmac_f32_dpp v91, v99, v209 row_shr:1 row_mask:0xf bank_mask:0xf
	v_fmac_f32_dpp v92, v100, v210 row_shr:2 row_mask:0xf bank_mask:0xf
	v_fmac_f32_dpp v93, v101, v211 row_shr:2 row_mask:0xf bank_mask:0xf
	v_fmac_f32_dpp v94, v102, v212 row_shr:2 row_mask:0xf bank_mask:0xf
	v_fmac_f32_dpp v95, v103, v213 row_shr:2 row_mask:0xf bank_mask:0xf
	v_fmac_f32_dpp v88, v96, v214 row_shr:2 row_mask:0xf bank_mask:0xf
	v_fmac_f32_dpp v89, v97, v215 row_shr:2 row_mask:0xf bank_mask:0xf
	v_fmac_f32_dpp v90, v98, v216 row_shr:2 row_mask:0xf bank_mask:0xf
	v_fmac_f32_dpp v91, v99, v217 row_shr:2 row_mask:0xf bank_mask:0xf
	v_fmac_f32_dpp v92, v246, v202 row_shl:15 row_mask:0xf bank_mask:0xf
	v_fmac_f32_dpp v93, v247, v203 row_shl:15 row_mask:0xf bank_mask:0xf
	v_fmac_f32_dpp v94, v248, v204 row_shl:15 row_mask:0xf bank_mask:0xf
	v_fmac_f32_dpp v95, v249, v205 row_shl:15 row_mask:0xf bank_mask:0xf
	v_fmac_f32_dpp v88, v250, v206 row_shl:15 row_mask:0xf bank_mask:0xf
	v_fmac_f32_dpp v89, v251, v207 row_shl:15 row_mask:0xf bank_mask:0xf
	v_fmac_f32_dpp v90, v252, v208 row_shl:15 row_mask:0xf bank_mask:0xf
	v_fmac_f32_dpp v91, v253, v209 row_shl:15 row_mask:0xf bank_mask:0xf
	v_fmac_f32_dpp v92, v246, v210 row_shl:14 row_mask:0xf bank_mask:0xf
	v_fmac_f32_dpp v93, v247, v211 row_shl:14 row_mask:0xf bank_mask:0xf
	v_fmac_f32_dpp v94, v248, v212 row_shl:14 row_mask:0xf bank_mask:0xf
	v_fmac_f32_dpp v95, v249, v213 row_shl:14 row_mask:0xf bank_mask:0xf
	v_fmac_f32_dpp v88, v250, v214 row_shl:14 row_mask:0xf bank_mask:0xf
	v_fmac_f32_dpp v89, v251, v215 row_shl:14 row_mask:0xf bank_mask:0xf
	v_fmac_f32_dpp v90, v252, v216 row_shl:14 row_mask:0xf bank_mask:0xf
	v_fmac_f32_dpp v91, v253, v217 row_shl:14 row_mask:0xf bank_mask:0xf
	v_mul_f32_e32 v246, 0xbfb8aa3b, v176
	v_mul_f32_e32 v247, 0xbfb8aa3b, v177
	v_mul_f32_e32 v248, 0xbfb8aa3b, v178
	v_mul_f32_e32 v249, 0xbfb8aa3b, v179
	v_mul_f32_e32 v250, 0xbfb8aa3b, v182
	v_mul_f32_e32 v251, 0xbfb8aa3b, v183
	v_mul_f32_e32 v252, 0xbfb8aa3b, v184
	v_mul_f32_e32 v253, 0xbfb8aa3b, v185
	v_exp_f32_e32 v246, v246
	v_exp_f32_e32 v247, v247
	v_exp_f32_e32 v248, v248
	v_exp_f32_e32 v249, v249
	v_exp_f32_e32 v250, v250
	v_exp_f32_e32 v251, v251
	v_exp_f32_e32 v252, v252
	v_exp_f32_e32 v253, v253
	v_add_f32_e32 v246, 1.0, v246
	v_add_f32_e32 v247, 1.0, v247
	v_add_f32_e32 v248, 1.0, v248
	v_add_f32_e32 v249, 1.0, v249
	v_add_f32_e32 v250, 1.0, v250
	v_add_f32_e32 v251, 1.0, v251
	v_add_f32_e32 v252, 1.0, v252
	v_add_f32_e32 v253, 1.0, v253
	v_rcp_f32_e32 v246, v246
	v_rcp_f32_e32 v247, v247
	v_rcp_f32_e32 v248, v248
	v_rcp_f32_e32 v249, v249
	v_rcp_f32_e32 v250, v250
	v_rcp_f32_e32 v251, v251
	v_rcp_f32_e32 v252, v252
	v_rcp_f32_e32 v253, v253
	v_mul_f32_e32 v176, v176, v246
	v_mul_f32_e32 v177, v177, v247
	v_mul_f32_e32 v178, v178, v248
	v_mul_f32_e32 v179, v179, v249
	v_mul_f32_e32 v182, v182, v250
	v_mul_f32_e32 v183, v183, v251
	v_mul_f32_e32 v184, v184, v252
	v_mul_f32_e32 v185, v185, v253
	v_mul_f32_e32 v176, v176, v8
	v_mul_f32_e32 v177, v177, v9
	v_mul_f32_e32 v178, v178, v10
	v_mul_f32_e32 v179, v179, v11
	v_mul_f32_e32 v182, v182, v128
	v_mul_f32_e32 v183, v183, v129
	v_mul_f32_e32 v184, v184, v130
	v_mul_f32_e32 v185, v185, v131
	v_cvt_pk_bf16_f32 v176, v176, v177
	v_cvt_pk_bf16_f32 v177, v178, v179
	v_cvt_pk_bf16_f32 v178, v182, v183
	v_cvt_pk_bf16_f32 v179, v184, v185
	v_add_u32_e32 v221, 0x84000, v245
	global_store_dwordx4 v221, v[176:179], s[12:13]
	v_mul_f32_e32 v246, 0xbfb8aa3b, v108
	v_mul_f32_e32 v247, 0xbfb8aa3b, v109
	v_mul_f32_e32 v248, 0xbfb8aa3b, v110
	v_mul_f32_e32 v249, 0xbfb8aa3b, v111
	v_mul_f32_e32 v250, 0xbfb8aa3b, v104
	v_mul_f32_e32 v251, 0xbfb8aa3b, v105
	v_mul_f32_e32 v252, 0xbfb8aa3b, v106
	v_mul_f32_e32 v253, 0xbfb8aa3b, v107
	v_exp_f32_e32 v246, v246
	v_exp_f32_e32 v247, v247
	v_exp_f32_e32 v248, v248
	v_exp_f32_e32 v249, v249
	v_exp_f32_e32 v250, v250
	v_exp_f32_e32 v251, v251
	v_exp_f32_e32 v252, v252
	v_exp_f32_e32 v253, v253
	v_add_f32_e32 v246, 1.0, v246
	v_add_f32_e32 v247, 1.0, v247
	v_add_f32_e32 v248, 1.0, v248
	v_add_f32_e32 v249, 1.0, v249
	v_add_f32_e32 v250, 1.0, v250
	v_add_f32_e32 v251, 1.0, v251
	v_add_f32_e32 v252, 1.0, v252
	v_add_f32_e32 v253, 1.0, v253
	v_rcp_f32_e32 v246, v246
	v_rcp_f32_e32 v247, v247
	v_rcp_f32_e32 v248, v248
	v_rcp_f32_e32 v249, v249
	v_rcp_f32_e32 v250, v250
	v_rcp_f32_e32 v251, v251
	v_rcp_f32_e32 v252, v252
	v_rcp_f32_e32 v253, v253
	v_mul_f32_e32 v108, v108, v246
	v_mul_f32_e32 v109, v109, v247
	v_mul_f32_e32 v110, v110, v248
	v_mul_f32_e32 v111, v111, v249
	v_mul_f32_e32 v104, v104, v250
	v_mul_f32_e32 v105, v105, v251
	v_mul_f32_e32 v106, v106, v252
	v_mul_f32_e32 v107, v107, v253
	v_mul_f32_e32 v108, v108, v76
	v_mul_f32_e32 v109, v109, v77
	v_mul_f32_e32 v110, v110, v78
	v_mul_f32_e32 v111, v111, v79
	v_mul_f32_e32 v104, v104, v72
	v_mul_f32_e32 v105, v105, v73
	v_mul_f32_e32 v106, v106, v74
	v_mul_f32_e32 v107, v107, v75
	v_cvt_pk_bf16_f32 v108, v108, v109
	v_cvt_pk_bf16_f32 v109, v110, v111
	v_cvt_pk_bf16_f32 v110, v104, v105
	v_cvt_pk_bf16_f32 v111, v106, v107
	v_add_u32_e32 v240, 0x58000, v245
	global_store_dwordx4 v240, v[108:111], s[12:13]
	v_mul_f32_e32 v246, 0xbfb8aa3b, v116
	v_mul_f32_e32 v247, 0xbfb8aa3b, v117
	v_mul_f32_e32 v248, 0xbfb8aa3b, v118
	v_mul_f32_e32 v249, 0xbfb8aa3b, v119
	v_mul_f32_e32 v250, 0xbfb8aa3b, v112
	v_mul_f32_e32 v251, 0xbfb8aa3b, v113
	v_mul_f32_e32 v252, 0xbfb8aa3b, v114
	v_mul_f32_e32 v253, 0xbfb8aa3b, v115
	v_exp_f32_e32 v246, v246
	v_exp_f32_e32 v247, v247
	v_exp_f32_e32 v248, v248
	v_exp_f32_e32 v249, v249
	v_exp_f32_e32 v250, v250
	v_exp_f32_e32 v251, v251
	v_exp_f32_e32 v252, v252
	v_exp_f32_e32 v253, v253
	v_add_f32_e32 v246, 1.0, v246
	v_add_f32_e32 v247, 1.0, v247
	v_add_f32_e32 v248, 1.0, v248
	v_add_f32_e32 v249, 1.0, v249
	v_add_f32_e32 v250, 1.0, v250
	v_add_f32_e32 v251, 1.0, v251
	v_add_f32_e32 v252, 1.0, v252
	v_add_f32_e32 v253, 1.0, v253
	v_rcp_f32_e32 v246, v246
	v_rcp_f32_e32 v247, v247
	v_rcp_f32_e32 v248, v248
	v_rcp_f32_e32 v249, v249
	v_rcp_f32_e32 v250, v250
	v_rcp_f32_e32 v251, v251
	v_rcp_f32_e32 v252, v252
	v_rcp_f32_e32 v253, v253
	v_mul_f32_e32 v116, v116, v246
	v_mul_f32_e32 v117, v117, v247
	v_mul_f32_e32 v118, v118, v248
	v_mul_f32_e32 v119, v119, v249
	v_mul_f32_e32 v112, v112, v250
	v_mul_f32_e32 v113, v113, v251
	v_mul_f32_e32 v114, v114, v252
	v_mul_f32_e32 v115, v115, v253
	v_mul_f32_e32 v116, v116, v84
	v_mul_f32_e32 v117, v117, v85
	v_mul_f32_e32 v118, v118, v86
	v_mul_f32_e32 v119, v119, v87
	v_mul_f32_e32 v112, v112, v80
	v_mul_f32_e32 v113, v113, v81
	v_mul_f32_e32 v114, v114, v82
	v_mul_f32_e32 v115, v115, v83
	v_cvt_pk_bf16_f32 v116, v116, v117
	v_cvt_pk_bf16_f32 v117, v118, v119
	v_cvt_pk_bf16_f32 v118, v112, v113
	v_cvt_pk_bf16_f32 v119, v114, v115
	v_add_u32_e32 v221, 0x2c000, v245
	global_store_dwordx4 v221, v[116:119], s[12:13]
	v_mul_f32_e32 v246, 0xbfb8aa3b, v124
	v_mul_f32_e32 v247, 0xbfb8aa3b, v125
	v_mul_f32_e32 v248, 0xbfb8aa3b, v126
	v_mul_f32_e32 v249, 0xbfb8aa3b, v127
	v_mul_f32_e32 v250, 0xbfb8aa3b, v120
	v_mul_f32_e32 v251, 0xbfb8aa3b, v121
	v_mul_f32_e32 v252, 0xbfb8aa3b, v122
	v_mul_f32_e32 v253, 0xbfb8aa3b, v123
	v_exp_f32_e32 v246, v246
	v_exp_f32_e32 v247, v247
	v_exp_f32_e32 v248, v248
	v_exp_f32_e32 v249, v249
	v_exp_f32_e32 v250, v250
	v_exp_f32_e32 v251, v251
	v_exp_f32_e32 v252, v252
	v_exp_f32_e32 v253, v253
	v_add_f32_e32 v246, 1.0, v246
	v_add_f32_e32 v247, 1.0, v247
	v_add_f32_e32 v248, 1.0, v248
	v_add_f32_e32 v249, 1.0, v249
	v_add_f32_e32 v250, 1.0, v250
	v_add_f32_e32 v251, 1.0, v251
	v_add_f32_e32 v252, 1.0, v252
	v_add_f32_e32 v253, 1.0, v253
	v_rcp_f32_e32 v246, v246
	v_rcp_f32_e32 v247, v247
	v_rcp_f32_e32 v248, v248
	v_rcp_f32_e32 v249, v249
	v_rcp_f32_e32 v250, v250
	v_rcp_f32_e32 v251, v251
	v_rcp_f32_e32 v252, v252
	v_rcp_f32_e32 v253, v253
	v_mul_f32_e32 v124, v124, v246
	v_mul_f32_e32 v125, v125, v247
	v_mul_f32_e32 v126, v126, v248
	v_mul_f32_e32 v127, v127, v249
	v_mul_f32_e32 v120, v120, v250
	v_mul_f32_e32 v121, v121, v251
	v_mul_f32_e32 v122, v122, v252
	v_mul_f32_e32 v123, v123, v253
	v_mul_f32_e32 v124, v124, v92
	v_mul_f32_e32 v125, v125, v93
	v_mul_f32_e32 v126, v126, v94
	v_mul_f32_e32 v127, v127, v95
	v_mul_f32_e32 v120, v120, v88
	v_mul_f32_e32 v121, v121, v89
	v_mul_f32_e32 v122, v122, v90
	v_mul_f32_e32 v123, v123, v91
	v_cvt_pk_bf16_f32 v124, v124, v125
	v_cvt_pk_bf16_f32 v125, v126, v127
	v_cvt_pk_bf16_f32 v126, v120, v121
	v_cvt_pk_bf16_f32 v127, v122, v123
	global_store_dwordx4 v245, v[124:127], s[12:13]
	s_mov_b32 exec_lo, 0xc000c000
	s_mov_b32 exec_hi, 0xc000c000
	ds_read_b128 v[246:249], v234 offset:4096
	ds_read_b128 v[250:253], v234 offset:4112
	s_mov_b64 exec, -1
	v_fma_f32 v176, v132, v44, v156
	v_fma_f32 v177, v133, v45, v157
	v_fma_f32 v178, v134, v46, v158
	v_fma_f32 v179, v135, v47, v159
	v_fma_f32 v182, v136, v40, v160
	v_fma_f32 v183, v137, v41, v161
	v_fma_f32 v184, v138, v42, v162
	v_fma_f32 v185, v139, v43, v163
	v_fmac_f32_dpp v176, v44, v140 row_shr:1 row_mask:0xf bank_mask:0xf
	v_fmac_f32_dpp v177, v45, v141 row_shr:1 row_mask:0xf bank_mask:0xf
	v_fmac_f32_dpp v178, v46, v142 row_shr:1 row_mask:0xf bank_mask:0xf
	v_fmac_f32_dpp v179, v47, v143 row_shr:1 row_mask:0xf bank_mask:0xf
	v_fmac_f32_dpp v182, v40, v144 row_shr:1 row_mask:0xf bank_mask:0xf
	v_fmac_f32_dpp v183, v41, v145 row_shr:1 row_mask:0xf bank_mask:0xf
	v_fmac_f32_dpp v184, v42, v146 row_shr:1 row_mask:0xf bank_mask:0xf
	v_fmac_f32_dpp v185, v43, v147 row_shr:1 row_mask:0xf bank_mask:0xf
	v_fmac_f32_dpp v176, v44, v148 row_shr:2 row_mask:0xf bank_mask:0xf
	v_fmac_f32_dpp v177, v45, v149 row_shr:2 row_mask:0xf bank_mask:0xf
	v_fmac_f32_dpp v178, v46, v150 row_shr:2 row_mask:0xf bank_mask:0xf
	v_fmac_f32_dpp v179, v47, v151 row_shr:2 row_mask:0xf bank_mask:0xf
	v_fmac_f32_dpp v182, v40, v152 row_shr:2 row_mask:0xf bank_mask:0xf
	v_fmac_f32_dpp v183, v41, v153 row_shr:2 row_mask:0xf bank_mask:0xf
	v_fmac_f32_dpp v184, v42, v154 row_shr:2 row_mask:0xf bank_mask:0xf
	v_fmac_f32_dpp v185, v43, v155 row_shr:2 row_mask:0xf bank_mask:0xf
	v_fmac_f32_dpp v176, v52, v140 row_shl:15 row_mask:0xf bank_mask:0xf
	v_fmac_f32_dpp v177, v53, v141 row_shl:15 row_mask:0xf bank_mask:0xf
	v_fmac_f32_dpp v178, v54, v142 row_shl:15 row_mask:0xf bank_mask:0xf
	v_fmac_f32_dpp v179, v55, v143 row_shl:15 row_mask:0xf bank_mask:0xf
	v_fmac_f32_dpp v182, v48, v144 row_shl:15 row_mask:0xf bank_mask:0xf
	v_fmac_f32_dpp v183, v49, v145 row_shl:15 row_mask:0xf bank_mask:0xf
	v_fmac_f32_dpp v184, v50, v146 row_shl:15 row_mask:0xf bank_mask:0xf
	v_fmac_f32_dpp v185, v51, v147 row_shl:15 row_mask:0xf bank_mask:0xf
	v_fmac_f32_dpp v176, v52, v148 row_shl:14 row_mask:0xf bank_mask:0xf
	v_fmac_f32_dpp v177, v53, v149 row_shl:14 row_mask:0xf bank_mask:0xf
	v_fmac_f32_dpp v178, v54, v150 row_shl:14 row_mask:0xf bank_mask:0xf
	v_fmac_f32_dpp v179, v55, v151 row_shl:14 row_mask:0xf bank_mask:0xf
	v_fmac_f32_dpp v182, v48, v152 row_shl:14 row_mask:0xf bank_mask:0xf
	v_fmac_f32_dpp v183, v49, v153 row_shl:14 row_mask:0xf bank_mask:0xf
	v_fmac_f32_dpp v184, v50, v154 row_shl:14 row_mask:0xf bank_mask:0xf
	v_fmac_f32_dpp v185, v51, v155 row_shl:14 row_mask:0xf bank_mask:0xf
	v_fma_f32 v44, v132, v52, v156
	v_fma_f32 v45, v133, v53, v157
	v_fma_f32 v46, v134, v54, v158
	v_fma_f32 v47, v135, v55, v159
	v_fma_f32 v40, v136, v48, v160
	v_fma_f32 v41, v137, v49, v161
	v_fma_f32 v42, v138, v50, v162
	v_fma_f32 v43, v139, v51, v163
	v_fmac_f32_dpp v44, v52, v140 row_shr:1 row_mask:0xf bank_mask:0xf
	v_fmac_f32_dpp v45, v53, v141 row_shr:1 row_mask:0xf bank_mask:0xf
	v_fmac_f32_dpp v46, v54, v142 row_shr:1 row_mask:0xf bank_mask:0xf
	v_fmac_f32_dpp v47, v55, v143 row_shr:1 row_mask:0xf bank_mask:0xf
	v_fmac_f32_dpp v40, v48, v144 row_shr:1 row_mask:0xf bank_mask:0xf
	v_fmac_f32_dpp v41, v49, v145 row_shr:1 row_mask:0xf bank_mask:0xf
	v_fmac_f32_dpp v42, v50, v146 row_shr:1 row_mask:0xf bank_mask:0xf
	v_fmac_f32_dpp v43, v51, v147 row_shr:1 row_mask:0xf bank_mask:0xf
	v_fmac_f32_dpp v44, v52, v148 row_shr:2 row_mask:0xf bank_mask:0xf
	v_fmac_f32_dpp v45, v53, v149 row_shr:2 row_mask:0xf bank_mask:0xf
	v_fmac_f32_dpp v46, v54, v150 row_shr:2 row_mask:0xf bank_mask:0xf
	v_fmac_f32_dpp v47, v55, v151 row_shr:2 row_mask:0xf bank_mask:0xf
	v_fmac_f32_dpp v40, v48, v152 row_shr:2 row_mask:0xf bank_mask:0xf
	v_fmac_f32_dpp v41, v49, v153 row_shr:2 row_mask:0xf bank_mask:0xf
	v_fmac_f32_dpp v42, v50, v154 row_shr:2 row_mask:0xf bank_mask:0xf
	v_fmac_f32_dpp v43, v51, v155 row_shr:2 row_mask:0xf bank_mask:0xf
	v_fmac_f32_dpp v44, v60, v140 row_shl:15 row_mask:0xf bank_mask:0xf
	v_fmac_f32_dpp v45, v61, v141 row_shl:15 row_mask:0xf bank_mask:0xf
	v_fmac_f32_dpp v46, v62, v142 row_shl:15 row_mask:0xf bank_mask:0xf
	v_fmac_f32_dpp v47, v63, v143 row_shl:15 row_mask:0xf bank_mask:0xf
	v_fmac_f32_dpp v40, v56, v144 row_shl:15 row_mask:0xf bank_mask:0xf
	v_fmac_f32_dpp v41, v57, v145 row_shl:15 row_mask:0xf bank_mask:0xf
	v_fmac_f32_dpp v42, v58, v146 row_shl:15 row_mask:0xf bank_mask:0xf
	v_fmac_f32_dpp v43, v59, v147 row_shl:15 row_mask:0xf bank_mask:0xf
	v_fmac_f32_dpp v44, v60, v148 row_shl:14 row_mask:0xf bank_mask:0xf
	v_fmac_f32_dpp v45, v61, v149 row_shl:14 row_mask:0xf bank_mask:0xf
	v_fmac_f32_dpp v46, v62, v150 row_shl:14 row_mask:0xf bank_mask:0xf
	v_fmac_f32_dpp v47, v63, v151 row_shl:14 row_mask:0xf bank_mask:0xf
	v_fmac_f32_dpp v40, v56, v152 row_shl:14 row_mask:0xf bank_mask:0xf
	v_fmac_f32_dpp v41, v57, v153 row_shl:14 row_mask:0xf bank_mask:0xf
	v_fmac_f32_dpp v42, v58, v154 row_shl:14 row_mask:0xf bank_mask:0xf
	v_fmac_f32_dpp v43, v59, v155 row_shl:14 row_mask:0xf bank_mask:0xf
	v_fma_f32 v52, v132, v60, v156
	v_fma_f32 v53, v133, v61, v157
	v_fma_f32 v54, v134, v62, v158
	v_fma_f32 v55, v135, v63, v159
	v_fma_f32 v48, v136, v56, v160
	v_fma_f32 v49, v137, v57, v161
	v_fma_f32 v50, v138, v58, v162
	v_fma_f32 v51, v139, v59, v163
	v_fmac_f32_dpp v52, v60, v140 row_shr:1 row_mask:0xf bank_mask:0xf
	v_fmac_f32_dpp v53, v61, v141 row_shr:1 row_mask:0xf bank_mask:0xf
	v_fmac_f32_dpp v54, v62, v142 row_shr:1 row_mask:0xf bank_mask:0xf
	v_fmac_f32_dpp v55, v63, v143 row_shr:1 row_mask:0xf bank_mask:0xf
	v_fmac_f32_dpp v48, v56, v144 row_shr:1 row_mask:0xf bank_mask:0xf
	v_fmac_f32_dpp v49, v57, v145 row_shr:1 row_mask:0xf bank_mask:0xf
	v_fmac_f32_dpp v50, v58, v146 row_shr:1 row_mask:0xf bank_mask:0xf
	v_fmac_f32_dpp v51, v59, v147 row_shr:1 row_mask:0xf bank_mask:0xf
	v_fmac_f32_dpp v52, v60, v148 row_shr:2 row_mask:0xf bank_mask:0xf
	v_fmac_f32_dpp v53, v61, v149 row_shr:2 row_mask:0xf bank_mask:0xf
	v_fmac_f32_dpp v54, v62, v150 row_shr:2 row_mask:0xf bank_mask:0xf
	v_fmac_f32_dpp v55, v63, v151 row_shr:2 row_mask:0xf bank_mask:0xf
	v_fmac_f32_dpp v48, v56, v152 row_shr:2 row_mask:0xf bank_mask:0xf
	v_fmac_f32_dpp v49, v57, v153 row_shr:2 row_mask:0xf bank_mask:0xf
	v_fmac_f32_dpp v50, v58, v154 row_shr:2 row_mask:0xf bank_mask:0xf
	v_fmac_f32_dpp v51, v59, v155 row_shr:2 row_mask:0xf bank_mask:0xf
	v_fmac_f32_dpp v52, v68, v140 row_shl:15 row_mask:0xf bank_mask:0xf
	v_fmac_f32_dpp v53, v69, v141 row_shl:15 row_mask:0xf bank_mask:0xf
	v_fmac_f32_dpp v54, v70, v142 row_shl:15 row_mask:0xf bank_mask:0xf
	v_fmac_f32_dpp v55, v71, v143 row_shl:15 row_mask:0xf bank_mask:0xf
	v_fmac_f32_dpp v48, v64, v144 row_shl:15 row_mask:0xf bank_mask:0xf
	v_fmac_f32_dpp v49, v65, v145 row_shl:15 row_mask:0xf bank_mask:0xf
	v_fmac_f32_dpp v50, v66, v146 row_shl:15 row_mask:0xf bank_mask:0xf
	v_fmac_f32_dpp v51, v67, v147 row_shl:15 row_mask:0xf bank_mask:0xf
	v_fmac_f32_dpp v52, v68, v148 row_shl:14 row_mask:0xf bank_mask:0xf
	v_fmac_f32_dpp v53, v69, v149 row_shl:14 row_mask:0xf bank_mask:0xf
	v_fmac_f32_dpp v54, v70, v150 row_shl:14 row_mask:0xf bank_mask:0xf
	v_fmac_f32_dpp v55, v71, v151 row_shl:14 row_mask:0xf bank_mask:0xf
	v_fmac_f32_dpp v48, v64, v152 row_shl:14 row_mask:0xf bank_mask:0xf
	v_fmac_f32_dpp v49, v65, v153 row_shl:14 row_mask:0xf bank_mask:0xf
	v_fmac_f32_dpp v50, v66, v154 row_shl:14 row_mask:0xf bank_mask:0xf
	v_fmac_f32_dpp v51, v67, v155 row_shl:14 row_mask:0xf bank_mask:0xf
	s_waitcnt lgkmcnt(0)
	v_fma_f32 v60, v132, v68, v156
	v_fma_f32 v61, v133, v69, v157
	v_fma_f32 v62, v134, v70, v158
	v_fma_f32 v63, v135, v71, v159
	v_fma_f32 v56, v136, v64, v160
	v_fma_f32 v57, v137, v65, v161
	v_fma_f32 v58, v138, v66, v162
	v_fma_f32 v59, v139, v67, v163
	v_fmac_f32_dpp v60, v68, v140 row_shr:1 row_mask:0xf bank_mask:0xf
	v_fmac_f32_dpp v61, v69, v141 row_shr:1 row_mask:0xf bank_mask:0xf
	v_fmac_f32_dpp v62, v70, v142 row_shr:1 row_mask:0xf bank_mask:0xf
	v_fmac_f32_dpp v63, v71, v143 row_shr:1 row_mask:0xf bank_mask:0xf
	v_fmac_f32_dpp v56, v64, v144 row_shr:1 row_mask:0xf bank_mask:0xf
	v_fmac_f32_dpp v57, v65, v145 row_shr:1 row_mask:0xf bank_mask:0xf
	v_fmac_f32_dpp v58, v66, v146 row_shr:1 row_mask:0xf bank_mask:0xf
	v_fmac_f32_dpp v59, v67, v147 row_shr:1 row_mask:0xf bank_mask:0xf
	v_fmac_f32_dpp v60, v68, v148 row_shr:2 row_mask:0xf bank_mask:0xf
	v_fmac_f32_dpp v61, v69, v149 row_shr:2 row_mask:0xf bank_mask:0xf
	v_fmac_f32_dpp v62, v70, v150 row_shr:2 row_mask:0xf bank_mask:0xf
	v_fmac_f32_dpp v63, v71, v151 row_shr:2 row_mask:0xf bank_mask:0xf
	v_fmac_f32_dpp v56, v64, v152 row_shr:2 row_mask:0xf bank_mask:0xf
	v_fmac_f32_dpp v57, v65, v153 row_shr:2 row_mask:0xf bank_mask:0xf
	v_fmac_f32_dpp v58, v66, v154 row_shr:2 row_mask:0xf bank_mask:0xf
	v_fmac_f32_dpp v59, v67, v155 row_shr:2 row_mask:0xf bank_mask:0xf
	v_fmac_f32_dpp v60, v246, v140 row_shl:15 row_mask:0xf bank_mask:0xf
	v_fmac_f32_dpp v61, v247, v141 row_shl:15 row_mask:0xf bank_mask:0xf
	v_fmac_f32_dpp v62, v248, v142 row_shl:15 row_mask:0xf bank_mask:0xf
	v_fmac_f32_dpp v63, v249, v143 row_shl:15 row_mask:0xf bank_mask:0xf
	v_fmac_f32_dpp v56, v250, v144 row_shl:15 row_mask:0xf bank_mask:0xf
	v_fmac_f32_dpp v57, v251, v145 row_shl:15 row_mask:0xf bank_mask:0xf
	v_fmac_f32_dpp v58, v252, v146 row_shl:15 row_mask:0xf bank_mask:0xf
	v_fmac_f32_dpp v59, v253, v147 row_shl:15 row_mask:0xf bank_mask:0xf
	v_fmac_f32_dpp v60, v246, v148 row_shl:14 row_mask:0xf bank_mask:0xf
	v_fmac_f32_dpp v61, v247, v149 row_shl:14 row_mask:0xf bank_mask:0xf
	v_fmac_f32_dpp v62, v248, v150 row_shl:14 row_mask:0xf bank_mask:0xf
	v_fmac_f32_dpp v63, v249, v151 row_shl:14 row_mask:0xf bank_mask:0xf
	v_fmac_f32_dpp v56, v250, v152 row_shl:14 row_mask:0xf bank_mask:0xf
	v_fmac_f32_dpp v57, v251, v153 row_shl:14 row_mask:0xf bank_mask:0xf
	v_fmac_f32_dpp v58, v252, v154 row_shl:14 row_mask:0xf bank_mask:0xf
	v_fmac_f32_dpp v59, v253, v155 row_shl:14 row_mask:0xf bank_mask:0xf
	s_lshl_b32 s37, s24, 8
	v_cndmask_b32_e64 v132, 0, 1, s[10:11]
	s_or_b32 s36, s37, 16
	s_or_b32 s25, s37, 32
	s_or_b32 s23, s37, 48
	v_mov_b32_e32 v156, 0
	v_cmp_ne_u32_e64 s[12:13], 1, v132
	s_andn2_b64 vcc, exec, s[10:11]
	v_mov_b32_e32 v157, 0
	v_mov_b32_e32 v158, 0
	v_mov_b32_e32 v159, 0
	v_mov_b32_e32 v160, 0
	v_mov_b32_e32 v161, 0
	v_mov_b32_e32 v162, 0
	v_mov_b32_e32 v163, 0
	v_mov_b32_e32 v148, 0
	v_mov_b32_e32 v149, 0
	v_mov_b32_e32 v150, 0
	v_mov_b32_e32 v151, 0
	v_mov_b32_e32 v152, 0
	v_mov_b32_e32 v153, 0
	v_mov_b32_e32 v154, 0
	v_mov_b32_e32 v155, 0
	v_mov_b32_e32 v140, 0
	v_mov_b32_e32 v141, 0
	v_mov_b32_e32 v142, 0
	v_mov_b32_e32 v143, 0
	v_mov_b32_e32 v144, 0
	v_mov_b32_e32 v145, 0
	v_mov_b32_e32 v146, 0
	v_mov_b32_e32 v147, 0
	v_mov_b32_e32 v132, 0
	v_mov_b32_e32 v133, 0
	v_mov_b32_e32 v134, 0
	v_mov_b32_e32 v135, 0
	v_mov_b32_e32 v136, 0
	v_mov_b32_e32 v137, 0
	v_mov_b32_e32 v138, 0
	v_mov_b32_e32 v139, 0
	s_cbranch_vccnz .LBB0_1072
	v_add_u32_e32 v132, s37, v3
	v_ashrrev_i32_e32 v133, 31, v132
	v_lshlrev_b64 v[132:133], 7, v[132:133]
	v_lshl_add_u64 v[132:133], v[170:171], 0, v[132:133]
	global_load_dwordx4 v[156:159], v[132:133], off
	global_load_dwordx4 v[160:163], v[132:133], off offset:16
	v_add_u32_e32 v132, s36, v3
	v_ashrrev_i32_e32 v133, 31, v132
	v_lshlrev_b64 v[132:133], 7, v[132:133]
	v_lshl_add_u64 v[132:133], v[170:171], 0, v[132:133]
	global_load_dwordx4 v[148:151], v[132:133], off
	global_load_dwordx4 v[152:155], v[132:133], off offset:16
	v_add_u32_e32 v132, s25, v3
	v_ashrrev_i32_e32 v133, 31, v132
	v_lshlrev_b64 v[132:133], 7, v[132:133]
	v_lshl_add_u64 v[132:133], v[170:171], 0, v[132:133]
	global_load_dwordx4 v[140:143], v[132:133], off
	global_load_dwordx4 v[144:147], v[132:133], off offset:16
	v_add_u32_e32 v132, s23, v3
	v_ashrrev_i32_e32 v133, 31, v132
	v_lshlrev_b64 v[132:133], 7, v[132:133]
	v_lshl_add_u64 v[136:137], v[170:171], 0, v[132:133]
	global_load_dwordx4 v[132:135], v[136:137], off
	s_nop 0
	global_load_dwordx4 v[136:139], v[136:137], off offset:16
.LBB0_1072:
	s_waitcnt lgkmcnt(0)
	s_and_b64 vcc, exec, s[12:13]
	s_mov_b32 exec_lo, 0xc000c000
	s_mov_b32 exec_hi, 0xc000c000
	ds_read_b128 v[246:249], v234 offset:4608
	ds_read_b128 v[250:253], v234 offset:4624
	s_mov_b64 exec, -1
	v_fma_f32 v68, v194, v12, v226
	v_fma_f32 v69, v195, v13, v227
	v_fma_f32 v70, v196, v14, v228
	v_fma_f32 v71, v197, v15, v229
	v_fma_f32 v64, v198, v4, v230
	v_fma_f32 v65, v199, v5, v231
	v_fma_f32 v66, v200, v6, v232
	v_fma_f32 v67, v201, v7, v233
	v_fmac_f32_dpp v68, v12, v202 row_shr:1 row_mask:0xf bank_mask:0xf
	v_fmac_f32_dpp v69, v13, v203 row_shr:1 row_mask:0xf bank_mask:0xf
	v_fmac_f32_dpp v70, v14, v204 row_shr:1 row_mask:0xf bank_mask:0xf
	v_fmac_f32_dpp v71, v15, v205 row_shr:1 row_mask:0xf bank_mask:0xf
	v_fmac_f32_dpp v64, v4, v206 row_shr:1 row_mask:0xf bank_mask:0xf
	v_fmac_f32_dpp v65, v5, v207 row_shr:1 row_mask:0xf bank_mask:0xf
	v_fmac_f32_dpp v66, v6, v208 row_shr:1 row_mask:0xf bank_mask:0xf
	v_fmac_f32_dpp v67, v7, v209 row_shr:1 row_mask:0xf bank_mask:0xf
	v_fmac_f32_dpp v68, v12, v210 row_shr:2 row_mask:0xf bank_mask:0xf
	v_fmac_f32_dpp v69, v13, v211 row_shr:2 row_mask:0xf bank_mask:0xf
	v_fmac_f32_dpp v70, v14, v212 row_shr:2 row_mask:0xf bank_mask:0xf
	v_fmac_f32_dpp v71, v15, v213 row_shr:2 row_mask:0xf bank_mask:0xf
	v_fmac_f32_dpp v64, v4, v214 row_shr:2 row_mask:0xf bank_mask:0xf
	v_fmac_f32_dpp v65, v5, v215 row_shr:2 row_mask:0xf bank_mask:0xf
	v_fmac_f32_dpp v66, v6, v216 row_shr:2 row_mask:0xf bank_mask:0xf
	v_fmac_f32_dpp v67, v7, v217 row_shr:2 row_mask:0xf bank_mask:0xf
	v_fmac_f32_dpp v68, v20, v202 row_shl:15 row_mask:0xf bank_mask:0xf
	v_fmac_f32_dpp v69, v21, v203 row_shl:15 row_mask:0xf bank_mask:0xf
	v_fmac_f32_dpp v70, v22, v204 row_shl:15 row_mask:0xf bank_mask:0xf
	v_fmac_f32_dpp v71, v23, v205 row_shl:15 row_mask:0xf bank_mask:0xf
	v_fmac_f32_dpp v64, v16, v206 row_shl:15 row_mask:0xf bank_mask:0xf
	v_fmac_f32_dpp v65, v17, v207 row_shl:15 row_mask:0xf bank_mask:0xf
	v_fmac_f32_dpp v66, v18, v208 row_shl:15 row_mask:0xf bank_mask:0xf
	v_fmac_f32_dpp v67, v19, v209 row_shl:15 row_mask:0xf bank_mask:0xf
	v_fmac_f32_dpp v68, v20, v210 row_shl:14 row_mask:0xf bank_mask:0xf
	v_fmac_f32_dpp v69, v21, v211 row_shl:14 row_mask:0xf bank_mask:0xf
	v_fmac_f32_dpp v70, v22, v212 row_shl:14 row_mask:0xf bank_mask:0xf
	v_fmac_f32_dpp v71, v23, v213 row_shl:14 row_mask:0xf bank_mask:0xf
	v_fmac_f32_dpp v64, v16, v214 row_shl:14 row_mask:0xf bank_mask:0xf
	v_fmac_f32_dpp v65, v17, v215 row_shl:14 row_mask:0xf bank_mask:0xf
	v_fmac_f32_dpp v66, v18, v216 row_shl:14 row_mask:0xf bank_mask:0xf
	v_fmac_f32_dpp v67, v19, v217 row_shl:14 row_mask:0xf bank_mask:0xf
	v_fma_f32 v12, v194, v20, v226
	v_fma_f32 v13, v195, v21, v227
	v_fma_f32 v14, v196, v22, v228
	v_fma_f32 v15, v197, v23, v229
	v_fma_f32 v4, v198, v16, v230
	v_fma_f32 v5, v199, v17, v231
	v_fma_f32 v6, v200, v18, v232
	v_fma_f32 v7, v201, v19, v233
	v_fmac_f32_dpp v12, v20, v202 row_shr:1 row_mask:0xf bank_mask:0xf
	v_fmac_f32_dpp v13, v21, v203 row_shr:1 row_mask:0xf bank_mask:0xf
	v_fmac_f32_dpp v14, v22, v204 row_shr:1 row_mask:0xf bank_mask:0xf
	v_fmac_f32_dpp v15, v23, v205 row_shr:1 row_mask:0xf bank_mask:0xf
	v_fmac_f32_dpp v4, v16, v206 row_shr:1 row_mask:0xf bank_mask:0xf
	v_fmac_f32_dpp v5, v17, v207 row_shr:1 row_mask:0xf bank_mask:0xf
	v_fmac_f32_dpp v6, v18, v208 row_shr:1 row_mask:0xf bank_mask:0xf
	v_fmac_f32_dpp v7, v19, v209 row_shr:1 row_mask:0xf bank_mask:0xf
	v_fmac_f32_dpp v12, v20, v210 row_shr:2 row_mask:0xf bank_mask:0xf
	v_fmac_f32_dpp v13, v21, v211 row_shr:2 row_mask:0xf bank_mask:0xf
	v_fmac_f32_dpp v14, v22, v212 row_shr:2 row_mask:0xf bank_mask:0xf
	v_fmac_f32_dpp v15, v23, v213 row_shr:2 row_mask:0xf bank_mask:0xf
	v_fmac_f32_dpp v4, v16, v214 row_shr:2 row_mask:0xf bank_mask:0xf
	v_fmac_f32_dpp v5, v17, v215 row_shr:2 row_mask:0xf bank_mask:0xf
	v_fmac_f32_dpp v6, v18, v216 row_shr:2 row_mask:0xf bank_mask:0xf
	v_fmac_f32_dpp v7, v19, v217 row_shr:2 row_mask:0xf bank_mask:0xf
	v_fmac_f32_dpp v12, v28, v202 row_shl:15 row_mask:0xf bank_mask:0xf
	v_fmac_f32_dpp v13, v29, v203 row_shl:15 row_mask:0xf bank_mask:0xf
	v_fmac_f32_dpp v14, v30, v204 row_shl:15 row_mask:0xf bank_mask:0xf
	v_fmac_f32_dpp v15, v31, v205 row_shl:15 row_mask:0xf bank_mask:0xf
	v_fmac_f32_dpp v4, v24, v206 row_shl:15 row_mask:0xf bank_mask:0xf
	v_fmac_f32_dpp v5, v25, v207 row_shl:15 row_mask:0xf bank_mask:0xf
	v_fmac_f32_dpp v6, v26, v208 row_shl:15 row_mask:0xf bank_mask:0xf
	v_fmac_f32_dpp v7, v27, v209 row_shl:15 row_mask:0xf bank_mask:0xf
	v_fmac_f32_dpp v12, v28, v210 row_shl:14 row_mask:0xf bank_mask:0xf
	v_fmac_f32_dpp v13, v29, v211 row_shl:14 row_mask:0xf bank_mask:0xf
	v_fmac_f32_dpp v14, v30, v212 row_shl:14 row_mask:0xf bank_mask:0xf
	v_fmac_f32_dpp v15, v31, v213 row_shl:14 row_mask:0xf bank_mask:0xf
	v_fmac_f32_dpp v4, v24, v214 row_shl:14 row_mask:0xf bank_mask:0xf
	v_fmac_f32_dpp v5, v25, v215 row_shl:14 row_mask:0xf bank_mask:0xf
	v_fmac_f32_dpp v6, v26, v216 row_shl:14 row_mask:0xf bank_mask:0xf
	v_fmac_f32_dpp v7, v27, v217 row_shl:14 row_mask:0xf bank_mask:0xf
	v_fma_f32 v20, v194, v28, v226
	v_fma_f32 v21, v195, v29, v227
	v_fma_f32 v22, v196, v30, v228
	v_fma_f32 v23, v197, v31, v229
	v_fma_f32 v16, v198, v24, v230
	v_fma_f32 v17, v199, v25, v231
	v_fma_f32 v18, v200, v26, v232
	v_fma_f32 v19, v201, v27, v233
	v_fmac_f32_dpp v20, v28, v202 row_shr:1 row_mask:0xf bank_mask:0xf
	v_fmac_f32_dpp v21, v29, v203 row_shr:1 row_mask:0xf bank_mask:0xf
	v_fmac_f32_dpp v22, v30, v204 row_shr:1 row_mask:0xf bank_mask:0xf
	v_fmac_f32_dpp v23, v31, v205 row_shr:1 row_mask:0xf bank_mask:0xf
	v_fmac_f32_dpp v16, v24, v206 row_shr:1 row_mask:0xf bank_mask:0xf
	v_fmac_f32_dpp v17, v25, v207 row_shr:1 row_mask:0xf bank_mask:0xf
	v_fmac_f32_dpp v18, v26, v208 row_shr:1 row_mask:0xf bank_mask:0xf
	v_fmac_f32_dpp v19, v27, v209 row_shr:1 row_mask:0xf bank_mask:0xf
	v_fmac_f32_dpp v20, v28, v210 row_shr:2 row_mask:0xf bank_mask:0xf
	v_fmac_f32_dpp v21, v29, v211 row_shr:2 row_mask:0xf bank_mask:0xf
	v_fmac_f32_dpp v22, v30, v212 row_shr:2 row_mask:0xf bank_mask:0xf
	v_fmac_f32_dpp v23, v31, v213 row_shr:2 row_mask:0xf bank_mask:0xf
	v_fmac_f32_dpp v16, v24, v214 row_shr:2 row_mask:0xf bank_mask:0xf
	v_fmac_f32_dpp v17, v25, v215 row_shr:2 row_mask:0xf bank_mask:0xf
	v_fmac_f32_dpp v18, v26, v216 row_shr:2 row_mask:0xf bank_mask:0xf
	v_fmac_f32_dpp v19, v27, v217 row_shr:2 row_mask:0xf bank_mask:0xf
	v_fmac_f32_dpp v20, v36, v202 row_shl:15 row_mask:0xf bank_mask:0xf
	v_fmac_f32_dpp v21, v37, v203 row_shl:15 row_mask:0xf bank_mask:0xf
	v_fmac_f32_dpp v22, v38, v204 row_shl:15 row_mask:0xf bank_mask:0xf
	v_fmac_f32_dpp v23, v39, v205 row_shl:15 row_mask:0xf bank_mask:0xf
	v_fmac_f32_dpp v16, v32, v206 row_shl:15 row_mask:0xf bank_mask:0xf
	v_fmac_f32_dpp v17, v33, v207 row_shl:15 row_mask:0xf bank_mask:0xf
	v_fmac_f32_dpp v18, v34, v208 row_shl:15 row_mask:0xf bank_mask:0xf
	v_fmac_f32_dpp v19, v35, v209 row_shl:15 row_mask:0xf bank_mask:0xf
	v_fmac_f32_dpp v20, v36, v210 row_shl:14 row_mask:0xf bank_mask:0xf
	v_fmac_f32_dpp v21, v37, v211 row_shl:14 row_mask:0xf bank_mask:0xf
	v_fmac_f32_dpp v22, v38, v212 row_shl:14 row_mask:0xf bank_mask:0xf
	v_fmac_f32_dpp v23, v39, v213 row_shl:14 row_mask:0xf bank_mask:0xf
	v_fmac_f32_dpp v16, v32, v214 row_shl:14 row_mask:0xf bank_mask:0xf
	v_fmac_f32_dpp v17, v33, v215 row_shl:14 row_mask:0xf bank_mask:0xf
	v_fmac_f32_dpp v18, v34, v216 row_shl:14 row_mask:0xf bank_mask:0xf
	v_fmac_f32_dpp v19, v35, v217 row_shl:14 row_mask:0xf bank_mask:0xf
	s_waitcnt lgkmcnt(0)
	v_fma_f32 v28, v194, v36, v226
	v_fma_f32 v29, v195, v37, v227
	v_fma_f32 v30, v196, v38, v228
	v_fma_f32 v31, v197, v39, v229
	v_fma_f32 v24, v198, v32, v230
	v_fma_f32 v25, v199, v33, v231
	v_fma_f32 v26, v200, v34, v232
	v_fma_f32 v27, v201, v35, v233
	v_fmac_f32_dpp v28, v36, v202 row_shr:1 row_mask:0xf bank_mask:0xf
	v_fmac_f32_dpp v29, v37, v203 row_shr:1 row_mask:0xf bank_mask:0xf
	v_fmac_f32_dpp v30, v38, v204 row_shr:1 row_mask:0xf bank_mask:0xf
	v_fmac_f32_dpp v31, v39, v205 row_shr:1 row_mask:0xf bank_mask:0xf
	v_fmac_f32_dpp v24, v32, v206 row_shr:1 row_mask:0xf bank_mask:0xf
	v_fmac_f32_dpp v25, v33, v207 row_shr:1 row_mask:0xf bank_mask:0xf
	v_fmac_f32_dpp v26, v34, v208 row_shr:1 row_mask:0xf bank_mask:0xf
	v_fmac_f32_dpp v27, v35, v209 row_shr:1 row_mask:0xf bank_mask:0xf
	v_fmac_f32_dpp v28, v36, v210 row_shr:2 row_mask:0xf bank_mask:0xf
	v_fmac_f32_dpp v29, v37, v211 row_shr:2 row_mask:0xf bank_mask:0xf
	v_fmac_f32_dpp v30, v38, v212 row_shr:2 row_mask:0xf bank_mask:0xf
	v_fmac_f32_dpp v31, v39, v213 row_shr:2 row_mask:0xf bank_mask:0xf
	v_fmac_f32_dpp v24, v32, v214 row_shr:2 row_mask:0xf bank_mask:0xf
	v_fmac_f32_dpp v25, v33, v215 row_shr:2 row_mask:0xf bank_mask:0xf
	v_fmac_f32_dpp v26, v34, v216 row_shr:2 row_mask:0xf bank_mask:0xf
	v_fmac_f32_dpp v27, v35, v217 row_shr:2 row_mask:0xf bank_mask:0xf
	v_fmac_f32_dpp v28, v246, v202 row_shl:15 row_mask:0xf bank_mask:0xf
	v_fmac_f32_dpp v29, v247, v203 row_shl:15 row_mask:0xf bank_mask:0xf
	v_fmac_f32_dpp v30, v248, v204 row_shl:15 row_mask:0xf bank_mask:0xf
	v_fmac_f32_dpp v31, v249, v205 row_shl:15 row_mask:0xf bank_mask:0xf
	v_fmac_f32_dpp v24, v250, v206 row_shl:15 row_mask:0xf bank_mask:0xf
	v_fmac_f32_dpp v25, v251, v207 row_shl:15 row_mask:0xf bank_mask:0xf
	v_fmac_f32_dpp v26, v252, v208 row_shl:15 row_mask:0xf bank_mask:0xf
	v_fmac_f32_dpp v27, v253, v209 row_shl:15 row_mask:0xf bank_mask:0xf
	v_fmac_f32_dpp v28, v246, v210 row_shl:14 row_mask:0xf bank_mask:0xf
	v_fmac_f32_dpp v29, v247, v211 row_shl:14 row_mask:0xf bank_mask:0xf
	v_fmac_f32_dpp v30, v248, v212 row_shl:14 row_mask:0xf bank_mask:0xf
	v_fmac_f32_dpp v31, v249, v213 row_shl:14 row_mask:0xf bank_mask:0xf
	v_fmac_f32_dpp v24, v250, v214 row_shl:14 row_mask:0xf bank_mask:0xf
	v_fmac_f32_dpp v25, v251, v215 row_shl:14 row_mask:0xf bank_mask:0xf
	v_fmac_f32_dpp v26, v252, v216 row_shl:14 row_mask:0xf bank_mask:0xf
	v_fmac_f32_dpp v27, v253, v217 row_shl:14 row_mask:0xf bank_mask:0xf
	s_cbranch_vccnz .LBB0_1082
	s_waitcnt vmcnt(0)
	v_add_f32_e32 v156, v156, v157
	v_add_f32_e32 v157, v158, v159
	v_add_f32_e32 v156, v156, v157
	v_add_f32_e32 v157, v160, v161
	v_add_f32_e32 v158, v162, v163
	v_add_f32_e32 v157, v157, v158
	v_add_f32_e32 v156, v156, v157
	ds_bpermute_b32 v157, v186, v156
	s_waitcnt lgkmcnt(0)
	v_add_f32_e32 v156, v156, v157
	ds_bpermute_b32 v157, v187, v156
	s_and_saveexec_b64 s[34:35], s[6:7]
	s_cbranch_execz .LBB0_1075
	s_waitcnt lgkmcnt(0)
	v_add_f32_e32 v156, v156, v157
	v_fmamk_f32 v156, v156, 0x3a000000, v218
	v_mul_f32_e32 v157, 0x4f800000, v156
	v_cmp_gt_f32_e32 vcc, s49, v156
	s_nop 1
	v_cndmask_b32_e32 v156, v156, v157, vcc
	v_sqrt_f32_e32 v157, v156
	s_nop 0
	v_add_u32_e32 v158, -1, v157
	v_fma_f32 v160, -v158, v157, v156
	v_add_u32_e32 v159, 1, v157
	v_cmp_ge_f32_e64 s[10:11], 0, v160
	s_nop 1
	v_cndmask_b32_e64 v158, v157, v158, s[10:11]
	v_fma_f32 v157, -v159, v157, v156
	v_cmp_lt_f32_e64 s[10:11], 0, v157
	s_nop 1
	v_cndmask_b32_e64 v157, v158, v159, s[10:11]
	v_mul_f32_e32 v158, 0x37800000, v157
	v_cndmask_b32_e32 v157, v157, v158, vcc
	v_cmp_class_f32_e32 vcc, v156, v220
	s_nop 1
	v_cndmask_b32_e32 v156, v157, v156, vcc
	v_div_scale_f32 v157, s[10:11], v156, v156, 1.0
	v_rcp_f32_e32 v158, v157
	s_nop 0
	v_fma_f32 v159, -v157, v158, 1.0
	v_fmac_f32_e32 v158, v159, v158
	v_div_scale_f32 v159, vcc, 1.0, v156, 1.0
	v_mul_f32_e32 v160, v159, v158
	v_fma_f32 v161, -v157, v160, v159
	v_fmac_f32_e32 v160, v161, v158
	v_fma_f32 v157, -v157, v160, v159
	v_div_fmas_f32 v157, v157, v158, v160
	v_div_fixup_f32 v156, v157, v156, 1.0
	ds_write_b32 v193, v156

.LBB0_1082:
	s_add_u32 s10, s42, 0xffffff00
	s_addc_u32 s11, s75, -1
	s_and_b64 vcc, exec, s[12:13]
	s_add_u32 s34, s18, 0x16000000
	s_addc_u32 s35, s19, 0
	v_mul_f32_e32 v246, 0xbfb8aa3b, v176
	v_mul_f32_e32 v247, 0xbfb8aa3b, v177
	v_mul_f32_e32 v248, 0xbfb8aa3b, v178
	v_mul_f32_e32 v249, 0xbfb8aa3b, v179
	v_mul_f32_e32 v250, 0xbfb8aa3b, v182
	v_mul_f32_e32 v251, 0xbfb8aa3b, v183
	v_mul_f32_e32 v252, 0xbfb8aa3b, v184
	v_mul_f32_e32 v253, 0xbfb8aa3b, v185
	v_exp_f32_e32 v246, v246
	v_exp_f32_e32 v247, v247
	v_exp_f32_e32 v248, v248
	v_exp_f32_e32 v249, v249
	v_exp_f32_e32 v250, v250
	v_exp_f32_e32 v251, v251
	v_exp_f32_e32 v252, v252
	v_exp_f32_e32 v253, v253
	v_add_f32_e32 v246, 1.0, v246
	v_add_f32_e32 v247, 1.0, v247
	v_add_f32_e32 v248, 1.0, v248
	v_add_f32_e32 v249, 1.0, v249
	v_add_f32_e32 v250, 1.0, v250
	v_add_f32_e32 v251, 1.0, v251
	v_add_f32_e32 v252, 1.0, v252
	v_add_f32_e32 v253, 1.0, v253
	v_rcp_f32_e32 v246, v246
	v_rcp_f32_e32 v247, v247
	v_rcp_f32_e32 v248, v248
	v_rcp_f32_e32 v249, v249
	v_rcp_f32_e32 v250, v250
	v_rcp_f32_e32 v251, v251
	v_rcp_f32_e32 v252, v252
	v_rcp_f32_e32 v253, v253
	v_mul_f32_e32 v176, v176, v246
	v_mul_f32_e32 v177, v177, v247
	v_mul_f32_e32 v178, v178, v248
	v_mul_f32_e32 v179, v179, v249
	v_mul_f32_e32 v182, v182, v250
	v_mul_f32_e32 v183, v183, v251
	v_mul_f32_e32 v184, v184, v252
	v_mul_f32_e32 v185, v185, v253
	v_mul_f32_e32 v176, v176, v68
	v_mul_f32_e32 v177, v177, v69
	v_mul_f32_e32 v178, v178, v70
	v_mul_f32_e32 v179, v179, v71
	v_mul_f32_e32 v182, v182, v64
	v_mul_f32_e32 v183, v183, v65
	v_mul_f32_e32 v184, v184, v66
	v_mul_f32_e32 v185, v185, v67
	v_cvt_pk_bf16_f32 v176, v176, v177
	v_cvt_pk_bf16_f32 v177, v178, v179
	v_cvt_pk_bf16_f32 v178, v182, v183
	v_cvt_pk_bf16_f32 v179, v184, v185
	v_add_u32_e32 v221, 0x1e4000, v245
	global_store_dwordx4 v221, v[176:179], s[34:35]
	v_mul_f32_e32 v246, 0xbfb8aa3b, v44
	v_mul_f32_e32 v247, 0xbfb8aa3b, v45
	v_mul_f32_e32 v248, 0xbfb8aa3b, v46
	v_mul_f32_e32 v249, 0xbfb8aa3b, v47
	v_mul_f32_e32 v250, 0xbfb8aa3b, v40
	v_mul_f32_e32 v251, 0xbfb8aa3b, v41
	v_mul_f32_e32 v252, 0xbfb8aa3b, v42
	v_mul_f32_e32 v253, 0xbfb8aa3b, v43
	v_exp_f32_e32 v246, v246
	v_exp_f32_e32 v247, v247
	v_exp_f32_e32 v248, v248
	v_exp_f32_e32 v249, v249
	v_exp_f32_e32 v250, v250
	v_exp_f32_e32 v251, v251
	v_exp_f32_e32 v252, v252
	v_exp_f32_e32 v253, v253
	v_add_f32_e32 v246, 1.0, v246
	v_add_f32_e32 v247, 1.0, v247
	v_add_f32_e32 v248, 1.0, v248
	v_add_f32_e32 v249, 1.0, v249
	v_add_f32_e32 v250, 1.0, v250
	v_add_f32_e32 v251, 1.0, v251
	v_add_f32_e32 v252, 1.0, v252
	v_add_f32_e32 v253, 1.0, v253
	v_rcp_f32_e32 v246, v246
	v_rcp_f32_e32 v247, v247
	v_rcp_f32_e32 v248, v248
	v_rcp_f32_e32 v249, v249
	v_rcp_f32_e32 v250, v250
	v_rcp_f32_e32 v251, v251
	v_rcp_f32_e32 v252, v252
	v_rcp_f32_e32 v253, v253
	v_mul_f32_e32 v44, v44, v246
	v_mul_f32_e32 v45, v45, v247
	v_mul_f32_e32 v46, v46, v248
	v_mul_f32_e32 v47, v47, v249
	v_mul_f32_e32 v40, v40, v250
	v_mul_f32_e32 v41, v41, v251
	v_mul_f32_e32 v42, v42, v252
	v_mul_f32_e32 v43, v43, v253
	v_mul_f32_e32 v44, v44, v12
	v_mul_f32_e32 v45, v45, v13
	v_mul_f32_e32 v46, v46, v14
	v_mul_f32_e32 v47, v47, v15
	v_mul_f32_e32 v40, v40, v4
	v_mul_f32_e32 v41, v41, v5
	v_mul_f32_e32 v42, v42, v6
	v_mul_f32_e32 v43, v43, v7
	v_cvt_pk_bf16_f32 v44, v44, v45
	v_cvt_pk_bf16_f32 v45, v46, v47
	v_cvt_pk_bf16_f32 v46, v40, v41
	v_cvt_pk_bf16_f32 v47, v42, v43
	v_add_u32_e32 v240, 0x1b8000, v245
	global_store_dwordx4 v240, v[44:47], s[34:35]
	v_mul_f32_e32 v246, 0xbfb8aa3b, v52
	v_mul_f32_e32 v247, 0xbfb8aa3b, v53
	v_mul_f32_e32 v248, 0xbfb8aa3b, v54
	v_mul_f32_e32 v249, 0xbfb8aa3b, v55
	v_mul_f32_e32 v250, 0xbfb8aa3b, v48
	v_mul_f32_e32 v251, 0xbfb8aa3b, v49
	v_mul_f32_e32 v252, 0xbfb8aa3b, v50
	v_mul_f32_e32 v253, 0xbfb8aa3b, v51
	v_exp_f32_e32 v246, v246
	v_exp_f32_e32 v247, v247
	v_exp_f32_e32 v248, v248
	v_exp_f32_e32 v249, v249
	v_exp_f32_e32 v250, v250
	v_exp_f32_e32 v251, v251
	v_exp_f32_e32 v252, v252
	v_exp_f32_e32 v253, v253
	v_add_f32_e32 v246, 1.0, v246
	v_add_f32_e32 v247, 1.0, v247
	v_add_f32_e32 v248, 1.0, v248
	v_add_f32_e32 v249, 1.0, v249
	v_add_f32_e32 v250, 1.0, v250
	v_add_f32_e32 v251, 1.0, v251
	v_add_f32_e32 v252, 1.0, v252
	v_add_f32_e32 v253, 1.0, v253
	v_rcp_f32_e32 v246, v246
	v_rcp_f32_e32 v247, v247
	v_rcp_f32_e32 v248, v248
	v_rcp_f32_e32 v249, v249
	v_rcp_f32_e32 v250, v250
	v_rcp_f32_e32 v251, v251
	v_rcp_f32_e32 v252, v252
	v_rcp_f32_e32 v253, v253
	v_mul_f32_e32 v52, v52, v246
	v_mul_f32_e32 v53, v53, v247
	v_mul_f32_e32 v54, v54, v248
	v_mul_f32_e32 v55, v55, v249
	v_mul_f32_e32 v48, v48, v250
	v_mul_f32_e32 v49, v49, v251
	v_mul_f32_e32 v50, v50, v252
	v_mul_f32_e32 v51, v51, v253
	v_mul_f32_e32 v52, v52, v20
	v_mul_f32_e32 v53, v53, v21
	v_mul_f32_e32 v54, v54, v22
	v_mul_f32_e32 v55, v55, v23
	v_mul_f32_e32 v48, v48, v16
	v_mul_f32_e32 v49, v49, v17
	v_mul_f32_e32 v50, v50, v18
	v_mul_f32_e32 v51, v51, v19
	v_cvt_pk_bf16_f32 v52, v52, v53
	v_cvt_pk_bf16_f32 v53, v54, v55
	v_cvt_pk_bf16_f32 v54, v48, v49
	v_cvt_pk_bf16_f32 v55, v50, v51
	v_add_u32_e32 v221, 0x18c000, v245
	global_store_dwordx4 v221, v[52:55], s[34:35]
	v_mul_f32_e32 v246, 0xbfb8aa3b, v60
	v_mul_f32_e32 v247, 0xbfb8aa3b, v61
	v_mul_f32_e32 v248, 0xbfb8aa3b, v62
	v_mul_f32_e32 v249, 0xbfb8aa3b, v63
	v_mul_f32_e32 v250, 0xbfb8aa3b, v56
	v_mul_f32_e32 v251, 0xbfb8aa3b, v57
	v_mul_f32_e32 v252, 0xbfb8aa3b, v58
	v_mul_f32_e32 v253, 0xbfb8aa3b, v59
	v_exp_f32_e32 v246, v246
	v_exp_f32_e32 v247, v247
	v_exp_f32_e32 v248, v248
	v_exp_f32_e32 v249, v249
	v_exp_f32_e32 v250, v250
	v_exp_f32_e32 v251, v251
	v_exp_f32_e32 v252, v252
	v_exp_f32_e32 v253, v253
	v_add_f32_e32 v246, 1.0, v246
	v_add_f32_e32 v247, 1.0, v247
	v_add_f32_e32 v248, 1.0, v248
	v_add_f32_e32 v249, 1.0, v249
	v_add_f32_e32 v250, 1.0, v250
	v_add_f32_e32 v251, 1.0, v251
	v_add_f32_e32 v252, 1.0, v252
	v_add_f32_e32 v253, 1.0, v253
	v_rcp_f32_e32 v246, v246
	v_rcp_f32_e32 v247, v247
	v_rcp_f32_e32 v248, v248
	v_rcp_f32_e32 v249, v249
	v_rcp_f32_e32 v250, v250
	v_rcp_f32_e32 v251, v251
	v_rcp_f32_e32 v252, v252
	v_rcp_f32_e32 v253, v253
	v_mul_f32_e32 v60, v60, v246
	v_mul_f32_e32 v61, v61, v247
	v_mul_f32_e32 v62, v62, v248
	v_mul_f32_e32 v63, v63, v249
	v_mul_f32_e32 v56, v56, v250
	v_mul_f32_e32 v57, v57, v251
	v_mul_f32_e32 v58, v58, v252
	v_mul_f32_e32 v59, v59, v253
	v_mul_f32_e32 v60, v60, v28
	v_mul_f32_e32 v61, v61, v29
	v_mul_f32_e32 v62, v62, v30
	v_mul_f32_e32 v63, v63, v31
	v_mul_f32_e32 v56, v56, v24
	v_mul_f32_e32 v57, v57, v25
	v_mul_f32_e32 v58, v58, v26
	v_mul_f32_e32 v59, v59, v27
	v_cvt_pk_bf16_f32 v60, v60, v61
	v_cvt_pk_bf16_f32 v61, v62, v63
	v_cvt_pk_bf16_f32 v62, v56, v57
	v_cvt_pk_bf16_f32 v63, v58, v59
	v_add_u32_e32 v240, 0x160000, v245
	global_store_dwordx4 v240, v[60:63], s[34:35]
	s_cbranch_vccnz .LBB0_1093
	s_waitcnt vmcnt(0)
	v_add_f32_e32 v4, v156, v157
	v_add_f32_e32 v5, v158, v159
	v_add_f32_e32 v4, v4, v5
	v_add_f32_e32 v5, v160, v161
	v_add_f32_e32 v6, v162, v163
	v_add_f32_e32 v5, v5, v6
	v_add_f32_e32 v4, v4, v5
	ds_bpermute_b32 v5, v186, v4
	s_waitcnt lgkmcnt(0)
	v_add_f32_e32 v4, v4, v5
	ds_bpermute_b32 v5, v187, v4
	s_and_saveexec_b64 s[12:13], s[6:7]
	s_cbranch_execz .LBB0_1085
	s_waitcnt lgkmcnt(0)
	v_add_f32_e32 v4, v4, v5
	v_fmamk_f32 v4, v4, 0x3a000000, v218
	v_mul_f32_e32 v5, 0x4f800000, v4
	v_cmp_gt_f32_e32 vcc, s49, v4
	s_nop 1
	v_cndmask_b32_e32 v4, v4, v5, vcc
	v_sqrt_f32_e32 v5, v4
	s_nop 0
	v_add_u32_e32 v6, -1, v5
	v_fma_f32 v8, -v6, v5, v4
	v_add_u32_e32 v7, 1, v5
	v_cmp_ge_f32_e64 s[10:11], 0, v8
	s_nop 1
	v_cndmask_b32_e64 v6, v5, v6, s[10:11]
	v_fma_f32 v5, -v7, v5, v4
	v_cmp_lt_f32_e64 s[10:11], 0, v5
	s_nop 1
	v_cndmask_b32_e64 v5, v6, v7, s[10:11]
	v_mul_f32_e32 v6, 0x37800000, v5
	v_cndmask_b32_e32 v5, v5, v6, vcc
	v_cmp_class_f32_e32 vcc, v4, v220
	s_nop 1
	v_cndmask_b32_e32 v4, v5, v4, vcc
	v_div_scale_f32 v5, s[10:11], v4, v4, 1.0
	v_rcp_f32_e32 v6, v5
	s_nop 0
	v_fma_f32 v7, -v5, v6, 1.0
	v_fmac_f32_e32 v6, v7, v6
	v_div_scale_f32 v7, vcc, 1.0, v4, 1.0
	v_mul_f32_e32 v8, v7, v6
	v_fma_f32 v9, -v5, v8, v7
	v_fmac_f32_e32 v8, v9, v6
	v_fma_f32 v5, -v5, v8, v7
	v_div_fmas_f32 v5, v5, v6, v8
	v_div_fixup_f32 v4, v5, v4, 1.0
	ds_write_b32 v193, v4 offset:256
